# P3 ssm_pass3: hoist 16 Du loads, carry SSM state across consecutive chunks per wave (skip Horner)
# speedup vs baseline: 1.0289x; 1.0289x over previous
.LBB0_381:
	v_lshrrev_b32_e32 v0, 11, v120
	v_bfe_u32 v1, v120, 3, 8
	v_mad_u32_u24 v0, v1, 12, v0
	v_and_b32_e32 v122, 63, v0
	v_lshrrev_b32_e32 v1, 6, v0
	v_mul_u32_u24_e32 v2, 0x2ab, v1
	v_lshrrev_b32_e32 v121, 13, v2
	v_mul_u32_u24_e32 v2, 12, v121
	v_sub_u32_e32 v1, v1, v2
	v_and_b32_e32 v3, 7, v120
	v_lshl_or_b32 v108, v1, 3, v3
	v_lshlrev_b32_e32 v0, 12, v121
	v_lshl_add_u32 v124, v122, 6, v0
	v_lshlrev_b32_e32 v68, 4, v108
	v_or_b32_e32 v0, v124, v198
	v_ashrrev_i32_e32 v69, 31, v68
	v_lshl_add_u64 v[70:71], v[68:69], 1, s[26:27]
	v_ashrrev_i32_e32 v1, 31, v0
	v_or_b32_e32 v6, 16, v0
	v_lshl_add_u64 v[2:3], v[70:71], 0, v[106:107]
	v_lshlrev_b64 v[4:5], 13, v[0:1]
	v_ashrrev_i32_e32 v7, 31, v6
	v_lshl_add_u64 v[4:5], v[2:3], 0, v[4:5]
	v_lshlrev_b64 v[6:7], 13, v[6:7]
	v_lshl_add_u64 v[6:7], v[2:3], 0, v[6:7]
	global_load_dwordx4 v[64:67], v[4:5], off
	global_load_dwordx4 v[60:63], v[6:7], off
	v_or_b32_e32 v4, 32, v0
	v_or_b32_e32 v0, 48, v0
	v_ashrrev_i32_e32 v5, 31, v4
	v_ashrrev_i32_e32 v1, 31, v0
	v_lshlrev_b64 v[4:5], 13, v[4:5]
	v_lshlrev_b64 v[0:1], 13, v[0:1]
	v_lshl_add_u64 v[4:5], v[2:3], 0, v[4:5]
	v_lshl_add_u64 v[0:1], v[2:3], 0, v[0:1]
	v_ashrrev_i32_e32 v109, 31, v108
	global_load_dwordx4 v[56:59], v[4:5], off
	global_load_dwordx4 v[20:23], v[0:1], off
	v_lshlrev_b64 v[0:1], 10, v[108:109]
	v_lshl_add_u64 v[0:1], v[78:79], 0, v[0:1]
	v_lshlrev_b64 v[2:3], 13, v[108:109]
	v_lshl_add_u64 v[4:5], v[80:81], 0, v[2:3]
	global_load_dwordx4 v[8:11], v[0:1], off
	global_load_dwordx4 v[52:55], v[4:5], off
	v_lshl_add_u64 v[0:1], v[82:83], 0, v[2:3]
	v_lshl_add_u64 v[4:5], v[84:85], 0, v[2:3]
	global_load_dwordx4 v[48:51], v[0:1], off
	global_load_dwordx4 v[44:47], v[4:5], off
	v_lshl_add_u64 v[0:1], v[86:87], 0, v[2:3]
	v_lshl_add_u64 v[4:5], v[88:89], 0, v[2:3]
	global_load_dwordx4 v[40:43], v[0:1], off
	global_load_dwordx4 v[36:39], v[4:5], off
	v_lshl_add_u64 v[0:1], v[90:91], 0, v[2:3]
	v_lshl_add_u64 v[4:5], v[92:93], 0, v[2:3]
	global_load_dwordx4 v[32:35], v[0:1], off
	global_load_dwordx4 v[28:31], v[4:5], off
	v_lshl_add_u64 v[0:1], v[94:95], 0, v[2:3]
	v_lshlrev_b64 v[2:3], 12, v[108:109]
	v_lshl_add_u64 v[2:3], v[96:97], 0, v[2:3]
	global_load_dwordx4 v[24:27], v[0:1], off
	global_load_dwordx4 v[16:19], v[2:3], off
	global_load_dwordx4 v[12:15], v[2:3], off offset:1024
	global_load_dwordx4 v[4:7], v[2:3], off offset:2048
	s_nop 0
	global_load_dwordx4 v[0:3], v[2:3], off offset:3072
	v_or_b32_e32 v110, v68, v198
	v_ashrrev_i32_e32 v111, 31, v110
	v_lshl_add_u64 v[110:111], v[110:111], 2, s[58:59]
	global_load_dword v123, v[110:111], off
	v_or_b32_e32 v170, v124, v235
	v_mov_b32_e32 v171, 0
	v_lshl_add_u64 v[168:169], v[70:71], 0, v[74:75]
	v_lshlrev_b64 v[170:171], 13, v[170:171]
	s_mov_b64 s[60:61], 0x2000
	s_mov_b64 s[40:41], 0x20000
	v_lshl_add_u64 v[168:169], v[168:169], 0, v[170:171]
	v_lshl_add_u64 v[170:171], v[168:169], 0, s[60:61]
	v_lshl_add_u64 v[172:173], v[170:171], 0, s[60:61]
	v_lshl_add_u64 v[174:175], v[172:173], 0, s[60:61]
	global_load_ushort v152, v[168:169], off
	global_load_ushort v153, v[170:171], off
	global_load_ushort v154, v[172:173], off
	global_load_ushort v155, v[174:175], off
	v_lshl_add_u64 v[168:169], v[168:169], 0, s[40:41]
	v_lshl_add_u64 v[170:171], v[168:169], 0, s[60:61]
	v_lshl_add_u64 v[172:173], v[170:171], 0, s[60:61]
	v_lshl_add_u64 v[174:175], v[172:173], 0, s[60:61]
	global_load_ushort v156, v[168:169], off
	global_load_ushort v157, v[170:171], off
	global_load_ushort v158, v[172:173], off
	global_load_ushort v159, v[174:175], off
	v_lshl_add_u64 v[168:169], v[168:169], 0, s[40:41]
	v_lshl_add_u64 v[170:171], v[168:169], 0, s[60:61]
	v_lshl_add_u64 v[172:173], v[170:171], 0, s[60:61]
	v_lshl_add_u64 v[174:175], v[172:173], 0, s[60:61]
	global_load_ushort v160, v[168:169], off
	global_load_ushort v161, v[170:171], off
	global_load_ushort v162, v[172:173], off
	global_load_ushort v163, v[174:175], off
	v_lshl_add_u64 v[168:169], v[168:169], 0, s[40:41]
	v_lshl_add_u64 v[170:171], v[168:169], 0, s[60:61]
	v_lshl_add_u64 v[172:173], v[170:171], 0, s[60:61]
	v_lshl_add_u64 v[174:175], v[172:173], 0, s[60:61]
	global_load_ushort v164, v[168:169], off
	global_load_ushort v165, v[170:171], off
	global_load_ushort v166, v[172:173], off
	global_load_ushort v167, v[174:175], off
	v_readfirstlane_b32 s60, v120
	s_cmp_lt_u32 s60, 0x800
	s_cbranch_scc1 .Lp3_horner
	v_cmp_ne_u32_e32 vcc, 0, v122
	s_nop 1
	v_cndmask_b32_e32 v125, 0, v254, vcc
	v_cndmask_b32_e32 v111, 0, v255, vcc
	s_branch .Lp3_after_horner
.Lp3_horner:
	v_lshlrev_b32_e32 v114, 6, v121
	v_cmp_lt_i32_e32 vcc, 7, v122
	v_mov_b32_e32 v125, 0
	v_mov_b32_e32 v111, 0
	v_mov_b32_e32 v126, 0
	s_and_saveexec_b64 s[38:39], vcc
	s_cbranch_execz .LBB0_385
	v_mad_i64_i32 v[110:111], s[40:41], v114, s46, v[108:109]
	v_lshlrev_b64 v[110:111], 9, v[110:111]
	v_lshl_add_u64 v[112:113], v[102:103], 0, v[110:111]
	v_mov_b32_e32 v125, 0
	s_mov_b32 s60, 0
	s_mov_b64 s[40:41], 0
	v_mov_b32_e32 v115, 0

.Lp3_after_horner:
	s_waitcnt vmcnt(28)
	v_mfma_f32_16x16x32_bf16 v[112:115], v[64:67], v[52:55], 0
	s_waitcnt vmcnt(27)
	v_mfma_f32_16x16x32_bf16 v[126:129], v[64:67], v[48:51], 0
	s_waitcnt vmcnt(26)
	v_mfma_f32_16x16x32_bf16 v[130:133], v[64:67], v[44:47], 0
	s_nop 3
	ds_write_b128 v73, v[112:115]
	s_waitcnt vmcnt(25)
	v_mfma_f32_16x16x32_bf16 v[134:137], v[64:67], v[40:43], 0
	ds_write_b128 v73, v[126:129] offset:1280
	ds_write_b128 v73, v[130:133] offset:2560
	s_nop 5
	ds_write_b128 v73, v[134:137] offset:3840
	s_waitcnt vmcnt(24)
	v_mfma_f32_16x16x32_bf16 v[138:141], v[64:67], v[36:39], 0
	s_waitcnt vmcnt(23)
	v_mfma_f32_16x16x32_bf16 v[112:115], v[64:67], v[32:35], 0
	s_waitcnt vmcnt(22)
	v_mfma_f32_16x16x32_bf16 v[126:129], v[64:67], v[28:31], 0
	s_nop 3
	ds_write_b128 v73, v[138:141] offset:5120
	s_nop 0
	ds_write_b128 v73, v[112:115] offset:6400
	s_nop 0
	ds_write_b128 v73, v[126:129] offset:7680
	s_waitcnt vmcnt(21)
	v_mfma_f32_16x16x32_bf16 v[64:67], v[64:67], v[24:27], 0
	v_mfma_f32_16x16x32_bf16 v[136:139], v[60:63], v[44:47], 0
	s_nop 6
	ds_write_b128 v73, v[64:67] offset:8960
	ds_read_b128 v[64:67], v77
	ds_read_b128 v[112:115], v77 offset:80
	s_waitcnt lgkmcnt(1)
	v_fma_f32 v10, -v9, v111, v64
	s_waitcnt lgkmcnt(0)
	v_fma_f32 v11, v9, v125, v112
	v_fmac_f32_e32 v10, v8, v125
	v_fmac_f32_e32 v11, v8, v111
	s_nop 0
	v_cvt_pk_bf16_f32 v64, v10, v11
	ds_write_b32 v118, v64 offset:10240
	v_fma_f32 v64, -v9, v11, v65
	v_fmac_f32_e32 v64, v8, v10
	v_fma_f32 v10, v9, v10, v113
	v_fmac_f32_e32 v10, v8, v11
	s_nop 0
	v_cvt_pk_bf16_f32 v11, v64, v10
	ds_write_b32 v118, v11 offset:10512
	v_fma_f32 v11, -v9, v10, v66
	v_fmac_f32_e32 v11, v8, v64
	v_fma_f32 v64, v9, v64, v114
	v_fmac_f32_e32 v64, v8, v10
	s_nop 0
	v_cvt_pk_bf16_f32 v10, v11, v64
	ds_write_b32 v118, v10 offset:10784
	v_fma_f32 v10, -v9, v64, v67
	v_fmac_f32_e32 v115, v9, v11
	v_fmac_f32_e32 v10, v8, v11
	v_fmac_f32_e32 v115, v8, v64
	s_nop 0
	v_cvt_pk_bf16_f32 v11, v10, v115
	ds_write_b32 v118, v11 offset:11056
	ds_read_b128 v[64:67], v77 offset:16
	ds_read_b128 v[110:113], v77 offset:96
	s_waitcnt lgkmcnt(1)
	v_fma_f32 v11, -v9, v115, v64
	v_fmac_f32_e32 v11, v8, v10
	s_waitcnt lgkmcnt(0)
	v_fma_f32 v10, v9, v10, v110
	v_fmac_f32_e32 v10, v8, v115
	s_nop 0
	v_cvt_pk_bf16_f32 v64, v11, v10
	ds_write_b32 v118, v64 offset:11328
	v_fma_f32 v64, -v9, v10, v65
	v_fmac_f32_e32 v64, v8, v11
	v_fma_f32 v11, v9, v11, v111
	v_fmac_f32_e32 v11, v8, v10
	s_nop 0
	v_cvt_pk_bf16_f32 v10, v64, v11
	ds_write_b32 v118, v10 offset:11600
	v_fma_f32 v10, -v9, v11, v66
	v_fmac_f32_e32 v10, v8, v64
	v_fma_f32 v64, v9, v64, v112
	v_fmac_f32_e32 v64, v8, v11
	s_nop 0
	v_cvt_pk_bf16_f32 v11, v10, v64
	ds_write_b32 v118, v11 offset:11872
	v_fma_f32 v11, -v9, v64, v67
	v_fmac_f32_e32 v113, v9, v10
	v_fmac_f32_e32 v11, v8, v10
	v_fmac_f32_e32 v113, v8, v64
	s_nop 0
	v_cvt_pk_bf16_f32 v10, v11, v113
	ds_write_b32 v118, v10 offset:12144
	ds_read_b128 v[64:67], v77 offset:32
	ds_read_b128 v[126:129], v77 offset:112
	s_waitcnt lgkmcnt(1)
	v_fma_f32 v10, -v9, v113, v64
	v_fmac_f32_e32 v10, v8, v11
	s_waitcnt lgkmcnt(0)
	v_fma_f32 v11, v9, v11, v126
	v_fmac_f32_e32 v11, v8, v113
	s_nop 0
	v_cvt_pk_bf16_f32 v64, v10, v11
	ds_write_b32 v118, v64 offset:12416
	v_fma_f32 v64, -v9, v11, v65
	v_fmac_f32_e32 v64, v8, v10
	v_fma_f32 v10, v9, v10, v127
	v_fmac_f32_e32 v10, v8, v11
	s_nop 0
	v_cvt_pk_bf16_f32 v11, v64, v10
	ds_write_b32 v118, v11 offset:12688
	v_fma_f32 v11, -v9, v10, v66
	v_fmac_f32_e32 v11, v8, v64
	v_fma_f32 v64, v9, v64, v128
	v_fmac_f32_e32 v64, v8, v10
	s_nop 0
	v_cvt_pk_bf16_f32 v10, v11, v64
	ds_write_b32 v118, v10 offset:12960
	v_fma_f32 v10, -v9, v64, v67
	v_fmac_f32_e32 v129, v9, v11
	v_fmac_f32_e32 v10, v8, v11
	v_fmac_f32_e32 v129, v8, v64
	s_nop 0
	v_cvt_pk_bf16_f32 v11, v10, v129
	ds_write_b32 v118, v11 offset:13232
	ds_read_b128 v[110:113], v77 offset:48
	ds_read_b128 v[64:67], v77 offset:128
	s_waitcnt lgkmcnt(1)
	v_fma_f32 v11, -v9, v129, v110
	v_fmac_f32_e32 v11, v8, v10
	s_waitcnt lgkmcnt(0)
	v_fma_f32 v10, v9, v10, v64
	v_fmac_f32_e32 v10, v8, v129
	s_nop 0
	v_cvt_pk_bf16_f32 v64, v11, v10
	ds_write_b32 v118, v64 offset:13504
	v_fma_f32 v64, -v9, v10, v111
	v_fmac_f32_e32 v64, v8, v11
	v_fma_f32 v11, v9, v11, v65
	v_fmac_f32_e32 v11, v8, v10
	s_nop 0
	v_cvt_pk_bf16_f32 v10, v64, v11
	ds_write_b32 v118, v10 offset:13776
	v_fma_f32 v10, -v9, v11, v112
	v_fmac_f32_e32 v10, v8, v64
	v_fma_f32 v64, v9, v64, v66
	v_fmac_f32_e32 v64, v8, v11
	s_nop 0
	v_fma_f32 v66, -v9, v64, v113
	v_fmac_f32_e32 v67, v9, v10
	v_cvt_pk_bf16_f32 v11, v10, v64
	v_fmac_f32_e32 v66, v8, v10
	v_fmac_f32_e32 v67, v8, v64
	ds_write_b32 v118, v11 offset:14048
	s_nop 0
	v_cvt_pk_bf16_f32 v10, v66, v67
	ds_write_b32 v118, v10 offset:14320
	ds_read_b128 v[110:113], v119 offset:10240
	ds_read_b128 v[126:129], v119 offset:10304
	s_waitcnt vmcnt(20) lgkmcnt(1)
	v_mfma_f32_16x16x32_bf16 v[112:115], v[110:113], v[16:19], 0
	v_or_b32_e32 v110, v124, v235
	v_ashrrev_i32_e32 v111, 31, v110
	v_lshl_add_u64 v[10:11], v[70:71], 0, v[74:75]
	v_lshlrev_b64 v[64:65], 13, v[110:111]
	v_lshl_add_u64 v[64:65], v[10:11], 0, v[64:65]
	ds_read_b128 v[132:135], v119 offset:10368
	ds_read_b128 v[140:143], v119 offset:10432
	s_waitcnt vmcnt(19) lgkmcnt(2)
	v_mfma_f32_16x16x32_bf16 v[112:115], v[126:129], v[12:15], v[112:115]
	s_waitcnt vmcnt(15)
	v_lshlrev_b32_e32 v109, 16, v152
	s_waitcnt lgkmcnt(1)
	v_mfma_f32_16x16x32_bf16 v[132:135], v[132:135], v[4:7], v[112:115]
	s_nop 3
	v_lshl_add_u64 v[112:113], v[68:69], 1, v[98:99]
	s_waitcnt lgkmcnt(0)
	v_mfma_f32_16x16x32_bf16 v[68:71], v[140:143], v[0:3], v[132:135]
	v_or_b32_e32 v114, 1, v110
	v_ashrrev_i32_e32 v115, 31, v114
	v_mad_i64_i32 v[64:65], s[38:39], v110, s56, v[112:113]
	v_lshlrev_b64 v[132:133], 13, v[114:115]
	s_nop 3
	v_fma_f32 v68, v123, v109, v68
	v_mul_f32_e32 v109, 0x3d372713, v68
	v_mul_f32_e32 v109, v68, v109
	v_fma_f32 v109, v68, v109, v68
	v_mul_f32_e32 v109, 0xbfcc422a, v109
	v_mul_f32_e32 v109, 0x3fb8aa3b, v109
	v_exp_f32_e32 v109, v109
	v_lshl_add_u64 v[140:141], v[10:11], 0, v[132:133]
	v_mfma_f32_16x16x32_bf16 v[124:127], v[60:63], v[52:55], 0
	v_add_f32_e32 v109, 1.0, v109
	v_div_scale_f32 v111, s[38:39], v109, v109, v68
	v_rcp_f32_e32 v115, v111
	v_div_scale_f32 v132, vcc, v68, v109, v68
	v_mfma_f32_16x16x32_bf16 v[128:131], v[60:63], v[48:51], 0
	v_fma_f32 v133, -v111, v115, 1.0
	v_fmac_f32_e32 v115, v133, v115
	v_mul_f32_e32 v133, v132, v115
	v_fma_f32 v134, -v111, v133, v132
	v_fmac_f32_e32 v133, v134, v115
	v_fma_f32 v111, -v111, v133, v132
	v_div_fmas_f32 v111, v111, v115, v133
	v_div_fixup_f32 v68, v111, v109, v68
	v_cvt_pk_bf16_f32 v68, v68, s0
	global_store_short v[64:65], v68, off
	v_or_b32_e32 v64, 2, v110
	v_mfma_f32_16x16x32_bf16 v[132:135], v[60:63], v[40:43], 0
	s_waitcnt vmcnt(15)
	v_lshlrev_b32_e32 v65, 16, v153
	v_fma_f32 v109, v123, v65, v69
	v_mul_f32_e32 v65, 0x3d372713, v109
	v_mul_f32_e32 v65, v109, v65
	v_fma_f32 v65, v109, v65, v109
	v_mul_f32_e32 v65, 0xbfcc422a, v65
	v_mul_f32_e32 v65, 0x3fb8aa3b, v65
	v_exp_f32_e32 v111, v65
	v_ashrrev_i32_e32 v65, 31, v64
	v_mad_i64_i32 v[68:69], s[38:39], v114, s56, v[112:113]
	v_lshlrev_b64 v[114:115], 13, v[64:65]
	v_add_f32_e32 v65, 1.0, v111
	v_div_scale_f32 v111, s[38:39], v65, v65, v109
	v_rcp_f32_e32 v144, v111
	v_div_scale_f32 v145, vcc, v109, v65, v109
	v_lshl_add_u64 v[114:115], v[10:11], 0, v[114:115]
	v_fma_f32 v146, -v111, v144, 1.0
	v_fmac_f32_e32 v144, v146, v144
	v_mul_f32_e32 v146, v145, v144
	v_fma_f32 v147, -v111, v146, v145
	v_fmac_f32_e32 v146, v147, v144
	v_fma_f32 v111, -v111, v146, v145
	v_div_fmas_f32 v111, v111, v144, v146
	v_div_fixup_f32 v65, v111, v65, v109
	v_cvt_pk_bf16_f32 v65, v65, s0
	global_store_short v[68:69], v65, off
	v_or_b32_e32 v68, 3, v110
	v_ashrrev_i32_e32 v69, 31, v68
	v_lshlrev_b64 v[114:115], 13, v[68:69]
	v_lshl_add_u64 v[114:115], v[10:11], 0, v[114:115]
	v_mfma_f32_16x16x32_bf16 v[140:143], v[60:63], v[36:39], 0
	s_waitcnt vmcnt(15)
	v_lshlrev_b32_e32 v65, 16, v154
	v_fma_f32 v70, v123, v65, v70
	v_mul_f32_e32 v65, 0x3d372713, v70
	v_mul_f32_e32 v65, v70, v65
	v_fma_f32 v65, v70, v65, v70
	v_mul_f32_e32 v65, 0xbfcc422a, v65
	v_mul_f32_e32 v65, 0x3fb8aa3b, v65
	v_exp_f32_e32 v109, v65
	v_mad_i64_i32 v[64:65], s[38:39], v64, s56, v[112:113]
	v_mfma_f32_16x16x32_bf16 v[144:147], v[60:63], v[32:35], 0
	v_add_f32_e32 v69, 1.0, v109
	v_div_scale_f32 v109, s[38:39], v69, v69, v70
	v_rcp_f32_e32 v111, v109
	v_div_scale_f32 v148, vcc, v70, v69, v70
	v_fma_f32 v149, -v109, v111, 1.0
	v_fmac_f32_e32 v111, v149, v111
	v_mul_f32_e32 v149, v148, v111
	v_fma_f32 v150, -v109, v149, v148
	v_fmac_f32_e32 v149, v150, v111
	v_fma_f32 v109, -v109, v149, v148
	v_div_fmas_f32 v109, v109, v111, v149
	v_div_fixup_f32 v69, v109, v69, v70
	v_cvt_pk_bf16_f32 v69, v69, s0
	global_store_short v[64:65], v69, off
	v_mfma_f32_16x16x32_bf16 v[148:151], v[60:63], v[28:31], 0
	s_waitcnt vmcnt(15)
	v_lshlrev_b32_e32 v64, 16, v155
	v_fmac_f32_e32 v71, v123, v64
	v_mul_f32_e32 v64, 0x3d372713, v71
	v_mul_f32_e32 v64, v71, v64
	v_fma_f32 v64, v71, v64, v71
	v_mul_f32_e32 v64, 0xbfcc422a, v64
	v_mul_f32_e32 v64, 0x3fb8aa3b, v64
	v_exp_f32_e32 v64, v64
	v_mfma_f32_16x16x32_bf16 v[60:63], v[60:63], v[24:27], 0
	v_add_f32_e32 v69, 1.0, v64
	v_div_scale_f32 v70, s[38:39], v69, v69, v71
	v_rcp_f32_e32 v109, v70
	v_mad_i64_i32 v[64:65], s[38:39], v68, s56, v[112:113]
	v_div_scale_f32 v68, vcc, v71, v69, v71
	v_fma_f32 v111, -v70, v109, 1.0
	v_fmac_f32_e32 v109, v111, v109
	v_mul_f32_e32 v111, v68, v109
	v_fma_f32 v114, -v70, v111, v68
	v_fmac_f32_e32 v111, v114, v109
	v_fma_f32 v68, -v70, v111, v68
	v_div_fmas_f32 v68, v68, v109, v111
	v_div_fixup_f32 v68, v68, v69, v71
	v_cvt_pk_bf16_f32 v68, v68, s0
	global_store_short v[64:65], v68, off
	ds_write_b128 v73, v[124:127]
	ds_write_b128 v73, v[128:131] offset:1280
	ds_write_b128 v73, v[136:139] offset:2560
	ds_write_b128 v73, v[132:135] offset:3840
	ds_write_b128 v73, v[140:143] offset:5120
	ds_write_b128 v73, v[144:147] offset:6400
	ds_write_b128 v73, v[148:151] offset:7680
	ds_write_b128 v73, v[60:63] offset:8960
	ds_read_b128 v[68:71], v77
	ds_read_b128 v[60:63], v77 offset:80
	v_mfma_f32_16x16x32_bf16 v[124:127], v[56:59], v[52:55], 0
	s_waitcnt lgkmcnt(1)
	v_fma_f32 v64, -v9, v67, v68
	s_waitcnt lgkmcnt(0)
	v_fma_f32 v60, v9, v66, v60
	v_fmac_f32_e32 v64, v8, v66
	v_fmac_f32_e32 v60, v8, v67
	v_mfma_f32_16x16x32_bf16 v[128:131], v[56:59], v[48:51], 0
	v_fma_f32 v66, -v9, v60, v69
	v_fma_f32 v61, v9, v64, v61
	v_cvt_pk_bf16_f32 v65, v64, v60
	v_fmac_f32_e32 v66, v8, v64
	v_fmac_f32_e32 v61, v8, v60
	ds_write_b32 v118, v65 offset:10240
	v_mfma_f32_16x16x32_bf16 v[132:135], v[56:59], v[44:47], 0
	v_fma_f32 v64, -v9, v61, v70
	v_fma_f32 v62, v9, v66, v62
	v_cvt_pk_bf16_f32 v60, v66, v61
	v_fmac_f32_e32 v64, v8, v66
	v_fmac_f32_e32 v62, v8, v61
	ds_write_b32 v118, v60 offset:10512
	v_mfma_f32_16x16x32_bf16 v[52:55], v[20:23], v[52:55], 0
	v_fma_f32 v61, -v9, v62, v71
	v_fmac_f32_e32 v63, v9, v64
	v_cvt_pk_bf16_f32 v60, v64, v62
	v_fmac_f32_e32 v61, v8, v64
	v_fmac_f32_e32 v63, v8, v62
	ds_write_b32 v118, v60 offset:10784
	v_mfma_f32_16x16x32_bf16 v[48:51], v[20:23], v[48:51], 0
	v_cvt_pk_bf16_f32 v60, v61, v63
	ds_write_b32 v118, v60 offset:11056
	ds_read_b128 v[68:71], v77 offset:16
	ds_read_b128 v[64:67], v77 offset:96
	v_mfma_f32_16x16x32_bf16 v[44:47], v[20:23], v[44:47], 0
	s_waitcnt lgkmcnt(1)
	v_fma_f32 v60, -v9, v63, v68
	s_waitcnt lgkmcnt(0)
	v_fma_f32 v62, v9, v61, v64
	v_fmac_f32_e32 v60, v8, v61
	v_fmac_f32_e32 v62, v8, v63
	s_nop 0
	v_fma_f32 v63, -v9, v62, v69
	v_fma_f32 v64, v9, v60, v65
	v_cvt_pk_bf16_f32 v61, v60, v62
	v_fmac_f32_e32 v63, v8, v60
	v_fmac_f32_e32 v64, v8, v62
	ds_write_b32 v118, v61 offset:11328
	s_nop 0
	v_fma_f32 v61, -v9, v64, v70
	v_fma_f32 v62, v9, v63, v66
	v_cvt_pk_bf16_f32 v60, v63, v64
	v_fmac_f32_e32 v61, v8, v63
	v_fmac_f32_e32 v62, v8, v64
	ds_write_b32 v118, v60 offset:11600
	s_nop 0
	v_fma_f32 v64, -v9, v62, v71
	v_fmac_f32_e32 v67, v9, v61
	v_cvt_pk_bf16_f32 v60, v61, v62
	v_fmac_f32_e32 v64, v8, v61
	v_fmac_f32_e32 v67, v8, v62
	ds_write_b32 v118, v60 offset:11872
	s_nop 0
	v_cvt_pk_bf16_f32 v60, v64, v67
	ds_write_b32 v118, v60 offset:12144
	ds_read_b128 v[60:63], v77 offset:32
	ds_read_b128 v[68:71], v77 offset:112
	s_waitcnt lgkmcnt(1)
	v_fma_f32 v60, -v9, v67, v60
	s_waitcnt lgkmcnt(0)
	v_fma_f32 v65, v9, v64, v68
	v_fmac_f32_e32 v60, v8, v64
	v_fmac_f32_e32 v65, v8, v67
	s_nop 0
	v_fma_f32 v61, -v9, v65, v61
	v_fma_f32 v66, v9, v60, v69
	v_cvt_pk_bf16_f32 v64, v60, v65
	v_fmac_f32_e32 v61, v8, v60
	v_fmac_f32_e32 v66, v8, v65
	ds_write_b32 v118, v64 offset:12416
	s_nop 0
	v_fma_f32 v62, -v9, v66, v62
	v_fma_f32 v64, v9, v61, v70
	v_cvt_pk_bf16_f32 v60, v61, v66
	v_fmac_f32_e32 v62, v8, v61
	v_fmac_f32_e32 v64, v8, v66
	ds_write_b32 v118, v60 offset:12688
	s_nop 0
	v_fma_f32 v68, -v9, v64, v63
	v_fmac_f32_e32 v71, v9, v62
	v_cvt_pk_bf16_f32 v60, v62, v64
	v_fmac_f32_e32 v68, v8, v62
	v_fmac_f32_e32 v71, v8, v64
	ds_write_b32 v118, v60 offset:12960
	s_nop 0
	v_cvt_pk_bf16_f32 v60, v68, v71
	ds_write_b32 v118, v60 offset:13232
	ds_read_b128 v[60:63], v77 offset:48
	ds_read_b128 v[64:67], v77 offset:128
	s_waitcnt lgkmcnt(1)
	v_fma_f32 v60, -v9, v71, v60
	s_waitcnt lgkmcnt(0)
	v_fma_f32 v64, v9, v68, v64
	v_fmac_f32_e32 v60, v8, v68
	v_fmac_f32_e32 v64, v8, v71
	s_nop 0
	v_fma_f32 v61, -v9, v64, v61
	v_fma_f32 v65, v9, v60, v65
	v_cvt_pk_bf16_f32 v68, v60, v64
	v_fmac_f32_e32 v61, v8, v60
	v_fmac_f32_e32 v65, v8, v64
	ds_write_b32 v118, v68 offset:13504
	v_mfma_f32_16x16x32_bf16 v[68:71], v[56:59], v[40:43], 0
	v_fma_f32 v62, -v9, v65, v62
	v_fma_f32 v64, v9, v61, v66
	v_cvt_pk_bf16_f32 v60, v61, v65
	v_fmac_f32_e32 v62, v8, v61
	v_fmac_f32_e32 v64, v8, v65
	ds_write_b32 v118, v60 offset:13776
	v_mfma_f32_16x16x32_bf16 v[40:43], v[20:23], v[40:43], 0
	v_fmac_f32_e32 v67, v9, v62
	v_cvt_pk_bf16_f32 v60, v62, v64
	v_fma_f32 v66, -v9, v64, v63
	v_fmac_f32_e32 v67, v8, v64
	v_or_b32_e32 v64, 16, v110
	v_fmac_f32_e32 v66, v8, v62
	v_ashrrev_i32_e32 v65, 31, v64
	ds_write_b32 v118, v60 offset:14048
	v_lshlrev_b64 v[114:115], 13, v[64:65]
	v_cvt_pk_bf16_f32 v60, v66, v67
	ds_write_b32 v118, v60 offset:14320
	v_lshl_add_u64 v[114:115], v[10:11], 0, v[114:115]
	ds_read_b128 v[60:63], v119 offset:10240
	ds_read_b128 v[136:139], v119 offset:10304
	s_waitcnt lgkmcnt(1)
	v_mfma_f32_16x16x32_bf16 v[60:63], v[60:63], v[16:19], 0
	ds_read_b128 v[140:143], v119 offset:10368
	v_or_b32_e32 v114, 17, v110
	v_ashrrev_i32_e32 v115, 31, v114
	s_waitcnt lgkmcnt(1)
	v_mfma_f32_16x16x32_bf16 v[60:63], v[136:139], v[12:15], v[60:63]
	ds_read_b128 v[136:139], v119 offset:10432
	s_waitcnt vmcnt(15)
	v_lshlrev_b32_e32 v65, 16, v156
	s_waitcnt lgkmcnt(1)
	v_mfma_f32_16x16x32_bf16 v[60:63], v[140:143], v[4:7], v[60:63]
	s_waitcnt lgkmcnt(0)
	v_mfma_f32_16x16x32_bf16 v[60:63], v[136:139], v[0:3], v[60:63]
	v_lshlrev_b64 v[136:137], 13, v[114:115]
	v_lshl_add_u64 v[136:137], v[10:11], 0, v[136:137]
	s_nop 5
	v_fma_f32 v60, v123, v65, v60
	v_mul_f32_e32 v65, 0x3d372713, v60
	v_mul_f32_e32 v65, v60, v65
	v_fma_f32 v65, v60, v65, v60
	v_mul_f32_e32 v65, 0xbfcc422a, v65
	v_mul_f32_e32 v65, 0x3fb8aa3b, v65
	v_exp_f32_e32 v109, v65
	v_mad_i64_i32 v[64:65], s[38:39], v64, s56, v[112:113]
	v_add_f32_e32 v109, 1.0, v109
	v_div_scale_f32 v111, s[38:39], v109, v109, v60
	v_rcp_f32_e32 v115, v111
	v_div_scale_f32 v138, vcc, v60, v109, v60
	v_fma_f32 v139, -v111, v115, 1.0
	v_fmac_f32_e32 v115, v139, v115
	v_mul_f32_e32 v139, v138, v115
	v_fma_f32 v140, -v111, v139, v138
	v_fmac_f32_e32 v139, v140, v115
	v_fma_f32 v111, -v111, v139, v138
	v_div_fmas_f32 v111, v111, v115, v139
	v_div_fixup_f32 v60, v111, v109, v60
	v_cvt_pk_bf16_f32 v60, v60, s0
	global_store_short v[64:65], v60, off
	v_or_b32_e32 v60, 18, v110
	v_mfma_f32_16x16x32_bf16 v[136:139], v[56:59], v[36:39], 0
	s_waitcnt vmcnt(15)
	v_lshlrev_b32_e32 v64, 16, v157
	v_fma_f32 v109, v123, v64, v61
	v_mul_f32_e32 v61, 0x3d372713, v109
	v_mul_f32_e32 v61, v109, v61
	v_fma_f32 v61, v109, v61, v109
	v_mul_f32_e32 v61, 0xbfcc422a, v61
	v_mul_f32_e32 v61, 0x3fb8aa3b, v61
	v_exp_f32_e32 v111, v61
	v_ashrrev_i32_e32 v61, 31, v60
	v_mad_i64_i32 v[64:65], s[38:39], v114, s56, v[112:113]
	v_lshlrev_b64 v[114:115], 13, v[60:61]
	v_add_f32_e32 v61, 1.0, v111
	v_div_scale_f32 v111, s[38:39], v61, v61, v109
	v_rcp_f32_e32 v140, v111
	v_div_scale_f32 v141, vcc, v109, v61, v109
	v_lshl_add_u64 v[114:115], v[10:11], 0, v[114:115]
	v_fma_f32 v142, -v111, v140, 1.0
	v_fmac_f32_e32 v140, v142, v140
	v_mul_f32_e32 v142, v141, v140
	v_fma_f32 v143, -v111, v142, v141
	v_fmac_f32_e32 v142, v143, v140
	v_fma_f32 v111, -v111, v142, v141
	v_div_fmas_f32 v111, v111, v140, v142
	v_div_fixup_f32 v61, v111, v61, v109
	v_cvt_pk_bf16_f32 v61, v61, s0
	global_store_short v[64:65], v61, off
	v_or_b32_e32 v64, 19, v110
	v_ashrrev_i32_e32 v65, 31, v64
	v_lshlrev_b64 v[114:115], 13, v[64:65]
	v_lshl_add_u64 v[114:115], v[10:11], 0, v[114:115]
	v_mfma_f32_16x16x32_bf16 v[140:143], v[56:59], v[32:35], 0
	s_waitcnt vmcnt(15)
	v_lshlrev_b32_e32 v61, 16, v158
	v_fma_f32 v62, v123, v61, v62
	v_mul_f32_e32 v61, 0x3d372713, v62
	v_mul_f32_e32 v61, v62, v61
	v_fma_f32 v61, v62, v61, v62
	v_mul_f32_e32 v61, 0xbfcc422a, v61
	v_mul_f32_e32 v61, 0x3fb8aa3b, v61
	v_exp_f32_e32 v109, v61
	v_mad_i64_i32 v[60:61], s[38:39], v60, s56, v[112:113]
	v_mfma_f32_16x16x32_bf16 v[36:39], v[20:23], v[36:39], 0
	v_add_f32_e32 v65, 1.0, v109
	v_div_scale_f32 v109, s[38:39], v65, v65, v62
	v_rcp_f32_e32 v111, v109
	v_div_scale_f32 v144, vcc, v62, v65, v62
	v_mfma_f32_16x16x32_bf16 v[32:35], v[20:23], v[32:35], 0
	v_fma_f32 v145, -v109, v111, 1.0
	v_fmac_f32_e32 v111, v145, v111
	v_mul_f32_e32 v145, v144, v111
	v_fma_f32 v146, -v109, v145, v144
	v_fmac_f32_e32 v145, v146, v111
	v_fma_f32 v109, -v109, v145, v144
	v_div_fmas_f32 v109, v109, v111, v145
	v_div_fixup_f32 v62, v109, v65, v62
	v_cvt_pk_bf16_f32 v62, v62, s0
	global_store_short v[60:61], v62, off
	v_mfma_f32_16x16x32_bf16 v[144:147], v[56:59], v[28:31], 0
	s_waitcnt vmcnt(15)
	v_lshlrev_b32_e32 v60, 16, v159
	v_fmac_f32_e32 v63, v123, v60
	v_mul_f32_e32 v60, 0x3d372713, v63
	v_mul_f32_e32 v60, v63, v60
	v_fma_f32 v60, v63, v60, v63
	v_mul_f32_e32 v60, 0xbfcc422a, v60
	v_mul_f32_e32 v60, 0x3fb8aa3b, v60
	v_exp_f32_e32 v60, v60
	v_mfma_f32_16x16x32_bf16 v[56:59], v[56:59], v[24:27], 0
	v_add_f32_e32 v62, 1.0, v60
	v_div_scale_f32 v65, s[38:39], v62, v62, v63
	v_rcp_f32_e32 v109, v65
	v_mad_i64_i32 v[60:61], s[38:39], v64, s56, v[112:113]
	v_div_scale_f32 v64, vcc, v63, v62, v63
	v_fma_f32 v111, -v65, v109, 1.0
	v_fmac_f32_e32 v109, v111, v109
	v_mul_f32_e32 v111, v64, v109
	v_fma_f32 v114, -v65, v111, v64
	v_fmac_f32_e32 v111, v114, v109
	v_fma_f32 v64, -v65, v111, v64
	v_div_fmas_f32 v64, v64, v109, v111
	v_div_fixup_f32 v62, v64, v62, v63
	v_cvt_pk_bf16_f32 v62, v62, s0
	global_store_short v[60:61], v62, off
	ds_write_b128 v73, v[124:127]
	ds_write_b128 v73, v[128:131] offset:1280
	ds_write_b128 v73, v[132:135] offset:2560
	ds_write_b128 v73, v[68:71] offset:3840
	ds_write_b128 v73, v[136:139] offset:5120
	ds_write_b128 v73, v[140:143] offset:6400
	ds_write_b128 v73, v[144:147] offset:7680
	ds_write_b128 v73, v[56:59] offset:8960
	ds_read_b128 v[60:63], v77
	ds_read_b128 v[56:59], v77 offset:80
	v_mfma_f32_16x16x32_bf16 v[28:31], v[20:23], v[28:31], 0
	s_waitcnt lgkmcnt(1)
	v_fma_f32 v60, -v9, v67, v60
	s_waitcnt lgkmcnt(0)
	v_fma_f32 v56, v9, v66, v56
	v_fmac_f32_e32 v60, v8, v66
	v_fmac_f32_e32 v56, v8, v67
	v_mfma_f32_16x16x32_bf16 v[20:23], v[20:23], v[24:27], 0
	v_fma_f32 v61, -v9, v56, v61
	v_fma_f32 v57, v9, v60, v57
	v_cvt_pk_bf16_f32 v64, v60, v56
	v_fmac_f32_e32 v61, v8, v60
	v_fmac_f32_e32 v57, v8, v56
	ds_write_b32 v118, v64 offset:10240
	s_nop 0
	v_fma_f32 v60, -v9, v57, v62
	v_fma_f32 v58, v9, v61, v58
	v_cvt_pk_bf16_f32 v56, v61, v57
	v_fmac_f32_e32 v60, v8, v61
	v_fmac_f32_e32 v58, v8, v57
	ds_write_b32 v118, v56 offset:10512
	s_nop 0
	v_fma_f32 v57, -v9, v58, v63
	v_fmac_f32_e32 v59, v9, v60
	v_cvt_pk_bf16_f32 v56, v60, v58
	v_fmac_f32_e32 v57, v8, v60
	v_fmac_f32_e32 v59, v8, v58
	ds_write_b32 v118, v56 offset:10784
	s_nop 0
	v_cvt_pk_bf16_f32 v56, v57, v59
	ds_write_b32 v118, v56 offset:11056
	ds_read_b128 v[64:67], v77 offset:16
	ds_read_b128 v[60:63], v77 offset:96
	s_waitcnt lgkmcnt(1)
	v_fma_f32 v56, -v9, v59, v64
	s_waitcnt lgkmcnt(0)
	v_fma_f32 v58, v9, v57, v60
	v_fmac_f32_e32 v56, v8, v57
	v_fmac_f32_e32 v58, v8, v59
	s_nop 0
	v_fma_f32 v59, -v9, v58, v65
	v_fma_f32 v60, v9, v56, v61
	v_cvt_pk_bf16_f32 v57, v56, v58
	v_fmac_f32_e32 v59, v8, v56
	v_fmac_f32_e32 v60, v8, v58
	ds_write_b32 v118, v57 offset:11328
	s_nop 0
	v_fma_f32 v57, -v9, v60, v66
	v_fma_f32 v58, v9, v59, v62
	v_cvt_pk_bf16_f32 v56, v59, v60
	v_fmac_f32_e32 v57, v8, v59
	v_fmac_f32_e32 v58, v8, v60
	ds_write_b32 v118, v56 offset:11600
	s_nop 0
	v_fma_f32 v60, -v9, v58, v67
	v_fmac_f32_e32 v63, v9, v57
	v_cvt_pk_bf16_f32 v56, v57, v58
	v_fmac_f32_e32 v60, v8, v57
	v_fmac_f32_e32 v63, v8, v58
	ds_write_b32 v118, v56 offset:11872
	s_nop 0
	v_cvt_pk_bf16_f32 v56, v60, v63
	ds_write_b32 v118, v56 offset:12144
	ds_read_b128 v[56:59], v77 offset:32
	ds_read_b128 v[64:67], v77 offset:112
	s_waitcnt lgkmcnt(1)
	v_fma_f32 v56, -v9, v63, v56
	s_waitcnt lgkmcnt(0)
	v_fma_f32 v61, v9, v60, v64
	v_fmac_f32_e32 v56, v8, v60
	v_fmac_f32_e32 v61, v8, v63
	s_nop 0
	v_fma_f32 v57, -v9, v61, v57
	v_fma_f32 v62, v9, v56, v65
	v_cvt_pk_bf16_f32 v60, v56, v61
	v_fmac_f32_e32 v57, v8, v56
	v_fmac_f32_e32 v62, v8, v61
	ds_write_b32 v118, v60 offset:12416
	s_nop 0
	v_fma_f32 v58, -v9, v62, v58
	v_fma_f32 v60, v9, v57, v66
	v_cvt_pk_bf16_f32 v56, v57, v62
	v_fmac_f32_e32 v58, v8, v57
	v_fmac_f32_e32 v60, v8, v62
	ds_write_b32 v118, v56 offset:12688
	s_nop 0
	v_fma_f32 v64, -v9, v60, v59
	v_fmac_f32_e32 v67, v9, v58
	v_cvt_pk_bf16_f32 v56, v58, v60
	v_fmac_f32_e32 v64, v8, v58
	v_fmac_f32_e32 v67, v8, v60
	ds_write_b32 v118, v56 offset:12960
	s_nop 0
	v_cvt_pk_bf16_f32 v56, v64, v67
	ds_write_b32 v118, v56 offset:13232
	ds_read_b128 v[56:59], v77 offset:48
	ds_read_b128 v[60:63], v77 offset:128
	s_waitcnt lgkmcnt(1)
	v_fma_f32 v56, -v9, v67, v56
	s_waitcnt lgkmcnt(0)
	v_fma_f32 v60, v9, v64, v60
	v_fmac_f32_e32 v56, v8, v64
	v_fmac_f32_e32 v60, v8, v67
	s_nop 0
	v_fma_f32 v57, -v9, v60, v57
	v_fma_f32 v61, v9, v56, v61
	v_cvt_pk_bf16_f32 v64, v56, v60
	v_fmac_f32_e32 v57, v8, v56
	v_fmac_f32_e32 v61, v8, v60
	ds_write_b32 v118, v64 offset:13504
	s_nop 0
	v_fma_f32 v58, -v9, v61, v58
	v_fma_f32 v60, v9, v57, v62
	v_cvt_pk_bf16_f32 v56, v57, v61
	v_fmac_f32_e32 v58, v8, v57
	v_fmac_f32_e32 v60, v8, v61
	ds_write_b32 v118, v56 offset:13776
	s_nop 0
	v_fma_f32 v62, -v9, v60, v59
	v_fmac_f32_e32 v63, v9, v58
	v_cvt_pk_bf16_f32 v56, v58, v60
	v_fmac_f32_e32 v62, v8, v58
	v_fmac_f32_e32 v63, v8, v60
	ds_write_b32 v118, v56 offset:14048
	v_or_b32_e32 v60, 32, v110
	v_cvt_pk_bf16_f32 v56, v62, v63
	ds_write_b32 v118, v56 offset:14320
	ds_read_b128 v[56:59], v119 offset:10240
	ds_read_b128 v[64:67], v119 offset:10304
	s_waitcnt lgkmcnt(1)
	v_mfma_f32_16x16x32_bf16 v[56:59], v[56:59], v[16:19], 0
	v_ashrrev_i32_e32 v61, 31, v60
	ds_read_b128 v[68:71], v119 offset:10368
	s_waitcnt lgkmcnt(1)
	v_mfma_f32_16x16x32_bf16 v[56:59], v[64:67], v[12:15], v[56:59]
	v_lshlrev_b64 v[64:65], 13, v[60:61]
	v_lshl_add_u64 v[114:115], v[10:11], 0, v[64:65]
	ds_read_b128 v[64:67], v119 offset:10432
	s_waitcnt lgkmcnt(1)
	v_mfma_f32_16x16x32_bf16 v[56:59], v[68:71], v[4:7], v[56:59]
	v_or_b32_e32 v68, 33, v110
	v_ashrrev_i32_e32 v69, 31, v68
	s_waitcnt vmcnt(15)
	v_lshlrev_b32_e32 v61, 16, v160
	s_waitcnt lgkmcnt(0)
	v_mfma_f32_16x16x32_bf16 v[56:59], v[64:67], v[0:3], v[56:59]
	v_lshlrev_b64 v[64:65], 13, v[68:69]
	v_lshl_add_u64 v[64:65], v[10:11], 0, v[64:65]
	s_nop 5
	v_fma_f32 v56, v123, v61, v56
	v_mul_f32_e32 v61, 0x3d372713, v56
	v_mul_f32_e32 v61, v56, v61
	v_fma_f32 v61, v56, v61, v56
	v_mul_f32_e32 v61, 0xbfcc422a, v61
	v_mul_f32_e32 v61, 0x3fb8aa3b, v61
	v_exp_f32_e32 v66, v61
	v_mad_i64_i32 v[60:61], s[38:39], v60, s56, v[112:113]
	v_add_f32_e32 v66, 1.0, v66
	v_div_scale_f32 v67, s[38:39], v66, v66, v56
	v_rcp_f32_e32 v69, v67
	v_div_scale_f32 v70, vcc, v56, v66, v56
	v_fma_f32 v71, -v67, v69, 1.0
	v_fmac_f32_e32 v69, v71, v69
	v_mul_f32_e32 v71, v70, v69
	v_fma_f32 v109, -v67, v71, v70
	v_fmac_f32_e32 v71, v109, v69
	v_fma_f32 v67, -v67, v71, v70
	v_div_fmas_f32 v67, v67, v69, v71
	v_div_fixup_f32 v56, v67, v66, v56
	v_cvt_pk_bf16_f32 v56, v56, s0
	global_store_short v[60:61], v56, off
	v_or_b32_e32 v56, 34, v110
	s_waitcnt vmcnt(15)
	v_lshlrev_b32_e32 v60, 16, v161
	v_fma_f32 v66, v123, v60, v57
	v_mul_f32_e32 v57, 0x3d372713, v66
	v_mul_f32_e32 v57, v66, v57
	v_fma_f32 v57, v66, v57, v66
	v_mul_f32_e32 v57, 0xbfcc422a, v57
	v_mul_f32_e32 v57, 0x3fb8aa3b, v57
	v_exp_f32_e32 v67, v57
	v_ashrrev_i32_e32 v57, 31, v56
	v_lshlrev_b64 v[64:65], 13, v[56:57]
	v_mad_i64_i32 v[60:61], s[38:39], v68, s56, v[112:113]
	v_add_f32_e32 v57, 1.0, v67
	v_div_scale_f32 v67, s[38:39], v57, v57, v66
	v_rcp_f32_e32 v68, v67
	v_div_scale_f32 v69, vcc, v66, v57, v66
	v_lshl_add_u64 v[64:65], v[10:11], 0, v[64:65]
	v_fma_f32 v70, -v67, v68, 1.0
	v_fmac_f32_e32 v68, v70, v68
	v_mul_f32_e32 v70, v69, v68
	v_fma_f32 v71, -v67, v70, v69
	v_fmac_f32_e32 v70, v71, v68
	v_fma_f32 v67, -v67, v70, v69
	v_div_fmas_f32 v67, v67, v68, v70
	v_div_fixup_f32 v57, v67, v57, v66
	v_cvt_pk_bf16_f32 v57, v57, s0
	global_store_short v[60:61], v57, off
	v_or_b32_e32 v60, 35, v110
	v_ashrrev_i32_e32 v61, 31, v60
	v_lshlrev_b64 v[64:65], 13, v[60:61]
	v_lshl_add_u64 v[64:65], v[10:11], 0, v[64:65]
	v_mad_i64_i32 v[24:25], s[38:39], v60, s56, v[112:113]
	s_waitcnt vmcnt(15)
	v_lshlrev_b32_e32 v57, 16, v162
	v_fma_f32 v58, v123, v57, v58
	v_mul_f32_e32 v57, 0x3d372713, v58
	v_mul_f32_e32 v57, v58, v57
	v_fma_f32 v57, v58, v57, v58
	v_mul_f32_e32 v57, 0xbfcc422a, v57
	v_mul_f32_e32 v57, 0x3fb8aa3b, v57
	v_exp_f32_e32 v66, v57
	v_mad_i64_i32 v[56:57], s[38:39], v56, s56, v[112:113]
	v_add_f32_e32 v61, 1.0, v66
	v_div_scale_f32 v66, s[38:39], v61, v61, v58
	v_rcp_f32_e32 v67, v66
	v_div_scale_f32 v68, vcc, v58, v61, v58
	v_fma_f32 v69, -v66, v67, 1.0
	v_fmac_f32_e32 v67, v69, v67
	v_mul_f32_e32 v69, v68, v67
	v_fma_f32 v70, -v66, v69, v68
	v_fmac_f32_e32 v69, v70, v67
	v_fma_f32 v66, -v66, v69, v68
	v_div_fmas_f32 v66, v66, v67, v69
	v_div_fixup_f32 v58, v66, v61, v58
	v_cvt_pk_bf16_f32 v58, v58, s0
	global_store_short v[56:57], v58, off
	s_waitcnt vmcnt(15)
	v_lshlrev_b32_e32 v56, 16, v163
	v_fmac_f32_e32 v59, v123, v56
	v_mul_f32_e32 v56, 0x3d372713, v59
	v_mul_f32_e32 v56, v59, v56
	v_fma_f32 v56, v59, v56, v59
	v_mul_f32_e32 v56, 0xbfcc422a, v56
	v_mul_f32_e32 v56, 0x3fb8aa3b, v56
	v_exp_f32_e32 v56, v56
	s_nop 0
	v_add_f32_e32 v26, 1.0, v56
	v_div_scale_f32 v27, s[38:39], v26, v26, v59
	v_rcp_f32_e32 v56, v27
	v_div_scale_f32 v57, vcc, v59, v26, v59
	v_fma_f32 v58, -v27, v56, 1.0
	v_fmac_f32_e32 v56, v58, v56
	v_mul_f32_e32 v58, v57, v56
	v_fma_f32 v60, -v27, v58, v57
	v_fmac_f32_e32 v58, v60, v56
	v_fma_f32 v27, -v27, v58, v57
	v_div_fmas_f32 v27, v27, v56, v58
	v_div_fixup_f32 v26, v27, v26, v59
	v_cvt_pk_bf16_f32 v26, v26, s0
	global_store_short v[24:25], v26, off
	ds_write_b128 v73, v[52:55]
	ds_write_b128 v73, v[48:51] offset:1280
	ds_write_b128 v73, v[44:47] offset:2560
	ds_write_b128 v73, v[40:43] offset:3840
	ds_write_b128 v73, v[36:39] offset:5120
	ds_write_b128 v73, v[32:35] offset:6400
	ds_write_b128 v73, v[28:31] offset:7680
	ds_write_b128 v73, v[20:23] offset:8960
	ds_read_b128 v[20:23], v77
	ds_read_b128 v[24:27], v77 offset:80
	s_waitcnt lgkmcnt(1)
	v_fma_f32 v20, -v9, v63, v20
	s_waitcnt lgkmcnt(0)
	v_fma_f32 v24, v9, v62, v24
	v_fmac_f32_e32 v20, v8, v62
	v_fmac_f32_e32 v24, v8, v63
	s_nop 0
	v_fma_f32 v21, -v9, v24, v21
	v_fma_f32 v25, v9, v20, v25
	v_cvt_pk_bf16_f32 v28, v20, v24
	v_fmac_f32_e32 v21, v8, v20
	v_fmac_f32_e32 v25, v8, v24
	ds_write_b32 v118, v28 offset:10240
	s_nop 0
	v_fma_f32 v22, -v9, v25, v22
	v_fma_f32 v24, v9, v21, v26
	v_cvt_pk_bf16_f32 v20, v21, v25
	v_fmac_f32_e32 v22, v8, v21
	v_fmac_f32_e32 v24, v8, v25
	ds_write_b32 v118, v20 offset:10512
	s_nop 0
	v_fma_f32 v25, -v9, v24, v23
	v_fmac_f32_e32 v27, v9, v22
	v_cvt_pk_bf16_f32 v20, v22, v24
	v_fmac_f32_e32 v25, v8, v22
	v_fmac_f32_e32 v27, v8, v24
	ds_write_b32 v118, v20 offset:10784
	s_nop 0
	v_cvt_pk_bf16_f32 v20, v25, v27
	ds_write_b32 v118, v20 offset:11056
	ds_read_b128 v[20:23], v77 offset:16
	ds_read_b128 v[28:31], v77 offset:96
	s_waitcnt lgkmcnt(1)
	v_fma_f32 v20, -v9, v27, v20
	s_waitcnt lgkmcnt(0)
	v_fma_f32 v24, v9, v25, v28
	v_fmac_f32_e32 v20, v8, v25
	v_fmac_f32_e32 v24, v8, v27
	s_nop 0
	v_fma_f32 v21, -v9, v24, v21
	v_fma_f32 v26, v9, v20, v29
	v_cvt_pk_bf16_f32 v25, v20, v24
	v_fmac_f32_e32 v21, v8, v20
	v_fmac_f32_e32 v26, v8, v24
	ds_write_b32 v118, v25 offset:11328
	s_nop 0
	v_fma_f32 v22, -v9, v26, v22
	v_fma_f32 v24, v9, v21, v30
	v_cvt_pk_bf16_f32 v20, v21, v26
	v_fmac_f32_e32 v22, v8, v21
	v_fmac_f32_e32 v24, v8, v26
	ds_write_b32 v118, v20 offset:11600
	s_nop 0
	v_fma_f32 v28, -v9, v24, v23
	v_fmac_f32_e32 v31, v9, v22
	v_cvt_pk_bf16_f32 v20, v22, v24
	v_fmac_f32_e32 v28, v8, v22
	v_fmac_f32_e32 v31, v8, v24
	ds_write_b32 v118, v20 offset:11872
	s_nop 0
	v_cvt_pk_bf16_f32 v20, v28, v31
	ds_write_b32 v118, v20 offset:12144
	ds_read_b128 v[20:23], v77 offset:32
	ds_read_b128 v[24:27], v77 offset:112
	s_waitcnt lgkmcnt(1)
	v_fma_f32 v20, -v9, v31, v20
	s_waitcnt lgkmcnt(0)
	v_fma_f32 v24, v9, v28, v24
	v_fmac_f32_e32 v20, v8, v28
	v_fmac_f32_e32 v24, v8, v31
	s_nop 0
	v_fma_f32 v21, -v9, v24, v21
	v_fma_f32 v25, v9, v20, v25
	v_cvt_pk_bf16_f32 v28, v20, v24
	v_fmac_f32_e32 v21, v8, v20
	v_fmac_f32_e32 v25, v8, v24
	ds_write_b32 v118, v28 offset:12416
	s_nop 0
	v_fma_f32 v22, -v9, v25, v22
	v_fma_f32 v24, v9, v21, v26
	v_cvt_pk_bf16_f32 v20, v21, v25
	v_fmac_f32_e32 v22, v8, v21
	v_fmac_f32_e32 v24, v8, v25
	ds_write_b32 v118, v20 offset:12688
	s_nop 0
	v_fma_f32 v25, -v9, v24, v23
	v_fmac_f32_e32 v27, v9, v22
	v_cvt_pk_bf16_f32 v20, v22, v24
	v_fmac_f32_e32 v25, v8, v22
	v_fmac_f32_e32 v27, v8, v24
	ds_write_b32 v118, v20 offset:12960
	s_nop 0
	v_cvt_pk_bf16_f32 v20, v25, v27
	ds_write_b32 v118, v20 offset:13232
	ds_read_b128 v[28:31], v77 offset:48
	ds_read_b128 v[20:23], v77 offset:128
	s_waitcnt lgkmcnt(1)
	v_fma_f32 v24, -v9, v27, v28
	s_waitcnt lgkmcnt(0)
	v_fma_f32 v20, v9, v25, v20
	v_fmac_f32_e32 v24, v8, v25
	v_fmac_f32_e32 v20, v8, v27
	s_nop 0
	v_fma_f32 v26, -v9, v20, v29
	v_fma_f32 v21, v9, v24, v21
	v_cvt_pk_bf16_f32 v25, v24, v20
	v_fmac_f32_e32 v26, v8, v24
	v_fmac_f32_e32 v21, v8, v20
	ds_write_b32 v118, v25 offset:13504
	s_nop 0
	v_fma_f32 v24, -v9, v21, v30
	v_fma_f32 v25, v9, v26, v22
	v_cvt_pk_bf16_f32 v20, v26, v21
	v_fmac_f32_e32 v24, v8, v26
	v_fmac_f32_e32 v25, v8, v21
	ds_write_b32 v118, v20 offset:13776
	s_nop 0
	v_fma_f32 v22, -v9, v25, v31
	v_fmac_f32_e32 v23, v9, v24
	v_cvt_pk_bf16_f32 v20, v24, v25
	v_fmac_f32_e32 v22, v8, v24
	v_fmac_f32_e32 v23, v8, v25
	ds_write_b32 v118, v20 offset:14048
	s_nop 0
	v_cvt_pk_bf16_f32 v8, v22, v23
	v_mov_b32_e32 v254, v22
	v_mov_b32_e32 v255, v23
	ds_write_b32 v118, v8 offset:14320
	ds_read_b128 v[24:27], v119 offset:10240
	ds_read_b128 v[28:31], v119 offset:10304
	s_waitcnt lgkmcnt(1)
	v_mfma_f32_16x16x32_bf16 v[16:19], v[24:27], v[16:19], 0
	v_or_b32_e32 v8, 48, v110
	v_ashrrev_i32_e32 v9, 31, v8
	ds_read_b128 v[24:27], v119 offset:10368
	s_waitcnt lgkmcnt(1)
	v_mfma_f32_16x16x32_bf16 v[12:15], v[28:31], v[12:15], v[16:19]
	s_nop 2
	v_lshlrev_b64 v[16:17], 13, v[8:9]
	v_lshl_add_u64 v[20:21], v[10:11], 0, v[16:17]
	ds_read_b128 v[16:19], v119 offset:10432
	s_waitcnt lgkmcnt(1)
	v_mfma_f32_16x16x32_bf16 v[4:7], v[24:27], v[4:7], v[12:15]
	s_waitcnt lgkmcnt(0)
	v_mfma_f32_16x16x32_bf16 v[0:3], v[16:19], v[0:3], v[4:7]
	s_nop 0
	v_or_b32_e32 v12, 49, v110
	v_ashrrev_i32_e32 v13, 31, v12
	s_nop 2
	v_lshlrev_b64 v[6:7], 13, v[12:13]
	v_lshl_add_u64 v[6:7], v[10:11], 0, v[6:7]
	s_waitcnt vmcnt(15)
	v_lshlrev_b32_e32 v4, 16, v164
	v_fma_f32 v0, v123, v4, v0
	v_mul_f32_e32 v4, 0x3d372713, v0
	v_mul_f32_e32 v4, v0, v4
	v_fma_f32 v4, v0, v4, v0
	v_mul_f32_e32 v4, 0xbfcc422a, v4
	v_mul_f32_e32 v4, 0x3fb8aa3b, v4
	v_exp_f32_e32 v9, v4
	v_mad_i64_i32 v[4:5], s[38:39], v8, s56, v[112:113]
	v_add_f32_e32 v8, 1.0, v9
	v_div_scale_f32 v9, s[38:39], v8, v8, v0
	v_rcp_f32_e32 v13, v9
	v_div_scale_f32 v14, vcc, v0, v8, v0
	v_fma_f32 v15, -v9, v13, 1.0
	v_fmac_f32_e32 v13, v15, v13
	v_mul_f32_e32 v15, v14, v13
	v_fma_f32 v16, -v9, v15, v14
	v_fmac_f32_e32 v15, v16, v13
	v_fma_f32 v9, -v9, v15, v14
	v_div_fmas_f32 v9, v9, v13, v15
	v_div_fixup_f32 v0, v9, v8, v0
	v_cvt_pk_bf16_f32 v0, v0, s0
	global_store_short v[4:5], v0, off
	v_or_b32_e32 v0, 50, v110
	s_waitcnt vmcnt(15)
	v_lshlrev_b32_e32 v4, 16, v165
	v_fma_f32 v8, v123, v4, v1
	v_mul_f32_e32 v1, 0x3d372713, v8
	v_mul_f32_e32 v1, v8, v1
	v_fma_f32 v1, v8, v1, v8
	v_mul_f32_e32 v1, 0xbfcc422a, v1
	v_mul_f32_e32 v1, 0x3fb8aa3b, v1
	v_exp_f32_e32 v9, v1
	v_ashrrev_i32_e32 v1, 31, v0
	v_lshlrev_b64 v[6:7], 13, v[0:1]
	v_mad_i64_i32 v[4:5], s[38:39], v12, s56, v[112:113]
	v_add_f32_e32 v1, 1.0, v9
	v_div_scale_f32 v9, s[38:39], v1, v1, v8
	v_rcp_f32_e32 v12, v9
	v_div_scale_f32 v13, vcc, v8, v1, v8
	v_lshl_add_u64 v[6:7], v[10:11], 0, v[6:7]
	v_fma_f32 v14, -v9, v12, 1.0
	v_fmac_f32_e32 v12, v14, v12
	v_mul_f32_e32 v14, v13, v12
	v_fma_f32 v15, -v9, v14, v13
	v_fmac_f32_e32 v14, v15, v12
	v_fma_f32 v9, -v9, v14, v13
	v_div_fmas_f32 v9, v9, v12, v14
	v_div_fixup_f32 v1, v9, v1, v8
	v_cvt_pk_bf16_f32 v1, v1, s0
	global_store_short v[4:5], v1, off
	v_or_b32_e32 v4, 51, v110
	v_ashrrev_i32_e32 v5, 31, v4
	v_lshlrev_b64 v[6:7], 13, v[4:5]
	v_lshl_add_u64 v[6:7], v[10:11], 0, v[6:7]
	s_waitcnt vmcnt(15)
	v_lshlrev_b32_e32 v1, 16, v166
	v_fma_f32 v2, v123, v1, v2
	v_mul_f32_e32 v1, 0x3d372713, v2
	v_mul_f32_e32 v1, v2, v1
	v_fma_f32 v1, v2, v1, v2
	v_mul_f32_e32 v1, 0xbfcc422a, v1
	v_mul_f32_e32 v1, 0x3fb8aa3b, v1
	v_exp_f32_e32 v8, v1
	v_mad_i64_i32 v[0:1], s[38:39], v0, s56, v[112:113]
	v_add_f32_e32 v5, 1.0, v8
	v_div_scale_f32 v8, s[38:39], v5, v5, v2
	v_rcp_f32_e32 v9, v8
	v_div_scale_f32 v10, vcc, v2, v5, v2
	v_fma_f32 v11, -v8, v9, 1.0
	v_fmac_f32_e32 v9, v11, v9
	v_mul_f32_e32 v11, v10, v9
	v_fma_f32 v12, -v8, v11, v10
	v_fmac_f32_e32 v11, v12, v9
	v_fma_f32 v8, -v8, v11, v10
	v_div_fmas_f32 v8, v8, v9, v11
	v_div_fixup_f32 v2, v8, v5, v2
	v_cvt_pk_bf16_f32 v2, v2, s0
	global_store_short v[0:1], v2, off
	s_waitcnt vmcnt(15)
	v_lshlrev_b32_e32 v0, 16, v167
	v_fmac_f32_e32 v3, v123, v0
	v_mul_f32_e32 v0, 0x3d372713, v3
	v_mul_f32_e32 v0, v3, v0
	v_fma_f32 v0, v3, v0, v3
	v_mul_f32_e32 v0, 0xbfcc422a, v0
	v_mul_f32_e32 v0, 0x3fb8aa3b, v0
	v_exp_f32_e32 v0, v0
	s_nop 0
	v_add_f32_e32 v2, 1.0, v0
	v_div_scale_f32 v5, s[38:39], v2, v2, v3
	v_rcp_f32_e32 v6, v5
	v_mad_i64_i32 v[0:1], s[38:39], v4, s56, v[112:113]
	v_div_scale_f32 v4, vcc, v3, v2, v3
	v_fma_f32 v7, -v5, v6, 1.0
	v_fmac_f32_e32 v6, v7, v6
	v_mul_f32_e32 v7, v4, v6
	v_fma_f32 v8, -v5, v7, v4
	v_fmac_f32_e32 v7, v8, v6
	v_fma_f32 v4, -v5, v7, v4
	v_div_fmas_f32 v4, v4, v6, v7
	v_div_fixup_f32 v2, v4, v2, v3
	v_cvt_pk_bf16_f32 v2, v2, s0
	global_store_short v[0:1], v2, off
	v_cmp_eq_u32_e32 vcc, 63, v122
	s_and_saveexec_b64 s[38:39], vcc
	s_cbranch_execz .LBB0_380
	v_mad_i32_i24 v0, v121, s46, v108
	v_ashrrev_i32_e32 v1, 31, v0
	v_lshlrev_b64 v[0:1], 9, v[0:1]
	v_lshl_add_u64 v[0:1], v[100:101], 0, v[0:1]
	global_store_dwordx2 v[0:1], v[22:23], off
	s_branch .LBB0_380

	.amdhsa_kernel _Z10fwd_kernel6Params
		.amdhsa_group_segment_fixed_size 0
		.amdhsa_private_segment_fixed_size 0
		.amdhsa_kernarg_size 512
		.amdhsa_user_sgpr_count 2
		.amdhsa_user_sgpr_dispatch_ptr 0
		.amdhsa_user_sgpr_queue_ptr 0
		.amdhsa_user_sgpr_kernarg_segment_ptr 1
		.amdhsa_user_sgpr_dispatch_id 0
		.amdhsa_user_sgpr_kernarg_preload_length 0
		.amdhsa_user_sgpr_kernarg_preload_offset 0
		.amdhsa_user_sgpr_private_segment_size 0
		.amdhsa_uses_dynamic_stack 0
		.amdhsa_enable_private_segment 0
		.amdhsa_system_sgpr_workgroup_id_x 1
		.amdhsa_system_sgpr_workgroup_id_y 0
		.amdhsa_system_sgpr_workgroup_id_z 0
		.amdhsa_system_sgpr_workgroup_info 0
		.amdhsa_system_vgpr_workitem_id 2
		.amdhsa_next_free_vgpr 256
		.amdhsa_next_free_sgpr 98
		.amdhsa_accum_offset 256
		.amdhsa_reserve_vcc 1
		.amdhsa_float_round_mode_32 0
		.amdhsa_float_round_mode_16_64 0
		.amdhsa_float_denorm_mode_32 3
		.amdhsa_float_denorm_mode_16_64 3
		.amdhsa_dx10_clamp 1
		.amdhsa_ieee_mode 1
		.amdhsa_fp16_overflow 0
		.amdhsa_tg_split 0
		.amdhsa_exception_fp_ieee_invalid_op 0
		.amdhsa_exception_fp_denorm_src 0
		.amdhsa_exception_fp_ieee_div_zero 0
		.amdhsa_exception_fp_ieee_overflow 0
		.amdhsa_exception_fp_ieee_underflow 0
		.amdhsa_exception_fp_ieee_inexact 0
		.amdhsa_exception_int_div_zero 0
	.end_amdhsa_kernel

amdhsa.kernels:
  - .agpr_count:     0
    .args:
      - .offset:         0
        .size:           256
        .value_kind:     by_value
      - .offset:         256
        .size:           4
        .value_kind:     hidden_block_count_x
      - .offset:         260
        .size:           4
        .value_kind:     hidden_block_count_y
      - .offset:         264
        .size:           4
        .value_kind:     hidden_block_count_z
      - .offset:         268
        .size:           2
        .value_kind:     hidden_group_size_x
      - .offset:         270
        .size:           2
        .value_kind:     hidden_group_size_y
      - .offset:         272
        .size:           2
        .value_kind:     hidden_group_size_z
      - .offset:         274
        .size:           2
        .value_kind:     hidden_remainder_x
      - .offset:         276
        .size:           2
        .value_kind:     hidden_remainder_y
      - .offset:         278
        .size:           2
        .value_kind:     hidden_remainder_z
      - .offset:         296
        .size:           8
        .value_kind:     hidden_global_offset_x
      - .offset:         304
        .size:           8
        .value_kind:     hidden_global_offset_y
      - .offset:         312
        .size:           8
        .value_kind:     hidden_global_offset_z
      - .offset:         320
        .size:           2
        .value_kind:     hidden_grid_dims
      - .offset:         344
        .size:           8
        .value_kind:     hidden_multigrid_sync_arg
      - .offset:         376
        .size:           4
        .value_kind:     hidden_dynamic_lds_size
    .group_segment_fixed_size: 0
    .kernarg_segment_align: 8
    .kernarg_segment_size: 512
    .language:       OpenCL C
    .language_version:
      - 2
      - 0
    .max_flat_workgroup_size: 512
    .name:           _Z10fwd_kernel6Params
    .private_segment_fixed_size: 0
    .sgpr_count:     104
    .sgpr_spill_count: 2
    .symbol:         _Z10fwd_kernel6Params.kd
    .uniform_work_group_size: 1
    .uses_dynamic_stack: false
    .vgpr_count:     256
    .vgpr_spill_count: 0
    .wavefront_size: 64
